# speedup vs baseline: 1.0609x; 1.0189x over previous
; #define STAGE(P, q) do { GLDS16(q[0], (unsigned char*)(P) + wid * 1024); GLDS16(q[1], (unsigned char*)(P) + wid * 1024 + 8192); \
;     q[0] += 128; q[1] += 128; asm volatile("" : "+v"(q[0]), "+v"(q[1])); } while (0)
; #define LDA(dst, b, h) _Pragma("unroll") for (int m = 0; m < 4; ++m) _Pragma("unroll") for (int k = 0; k < 2; ++k) \
;     dst[m][k] = *(const bf16x8*)((const unsigned char*)SA(b, h) + lds_byte1(wr * 64 + m * 16 + fr, k * 32 + fq * 8))
; #define LDB(dst, b, h) _Pragma("unroll") for (int n = 0; n < 2; ++n) _Pragma("unroll") for (int k = 0; k < 2; ++k) \
;     dst[n][k] = *(const bf16x8*)((const unsigned char*)SB(b, h) + lds_byte1(wc * 32 + n * 16 + fr, k * 32 + fq * 8))
; #define MMA(ai, bj, At_, Bt_) do { __builtin_amdgcn_s_setprio(1); \
;     _Pragma("unroll") for (int m = 0; m < 4; ++m) _Pragma("unroll") for (int n = 0; n < 2; ++n) _Pragma("unroll") for (int k = 0; k < 2; ++k) \
;       acc[ai][bj][m][n] = mfma16(At_[m][k], Bt_[n][k], acc[ai][bj][m][n]); \
;     __builtin_amdgcn_s_setprio(0); } while (0)
; #define WAIT_V(n) asm volatile("s_waitcnt vmcnt(" #n ")" ::: "memory")
; #define WAIT_L(n) asm volatile("s_waitcnt lgkmcnt(" #n ")" ::: "memory")
; #define BAR __builtin_amdgcn_s_barrier()
; DEV void gemm_tile(const u16* __restrict__ A, const u16* __restrict__ Bt, u16* __restrict__ C, int N, int K,
;                    int brow, int bcol, unsigned char* smem, int epi, const GateEpi& ge) {
;     ...
;   STAGE(SB(0, 0), qB0); STAGE(SA(0, 0), qA0);
;   STAGE(SB(0, 1), qB1); STAGE(SA(0, 1), qA1);
;   if (wr == 1) BAR;
;   WAIT_V(4); BAR;
;   STAGE(SB(1, 0), qB0); STAGE(SA(1, 0), qA0); STAGE(SB(1, 1), qB1);
;     ...
;   { LDB(B0, 0, 0); LDA(At, 0, 0); STAGE(SA(1, 1), qA1);
;     BAR; WAIT_L(0); MMA(0, 0, At, B0); BAR;
;     LDB(B1, 0, 1); BAR; WAIT_L(0); MMA(0, 1, At, B1); BAR;
;     LDA(At, 0, 1); WAIT_V(4); BAR; WAIT_L(0); MMA(1, 0, At, B0); MMA(1, 1, At, B1); BAR; }
;   { LDB(B0, 1, 0); LDA(At, 1, 0); WAIT_V(2); BAR; WAIT_L(0); MMA(0, 0, At, B0); BAR;
;     LDB(B1, 1, 1); WAIT_V(0); BAR; WAIT_L(0); MMA(0, 1, At, B1); BAR;
;     LDA(At, 1, 1); BAR; WAIT_L(0); MMA(1, 0, At, B0); MMA(1, 1, At, B1); BAR; }
.Lwdma_skip_last:
	s_waitcnt lgkmcnt(8)
	s_barrier
	s_waitcnt lgkmcnt(0)
	s_setprio 1
	s_waitcnt lgkmcnt(0)
	v_mfma_f32_16x16x32_bf16 v[124:127], v[156:159], v[192:195], v[124:127]
	v_mfma_f32_16x16x32_bf16 v[120:123], v[184:187], v[192:195], v[120:123]
	v_mfma_f32_16x16x32_bf16 v[116:119], v[156:159], v[200:203], v[116:119]
	v_mfma_f32_16x16x32_bf16 v[112:115], v[184:187], v[200:203], v[112:115]
	v_mfma_f32_16x16x32_bf16 v[108:111], v[156:159], v[208:211], v[108:111]
	v_mfma_f32_16x16x32_bf16 v[104:107], v[184:187], v[208:211], v[104:107]
	v_mfma_f32_16x16x32_bf16 v[100:103], v[156:159], v[216:219], v[100:103]
	v_mfma_f32_16x16x32_bf16 v[96:99], v[184:187], v[216:219], v[96:99]
	v_mfma_f32_16x16x32_bf16 v[124:127], v[180:183], v[196:199], v[124:127]
	v_mfma_f32_16x16x32_bf16 v[120:123], v[188:191], v[196:199], v[120:123]
	v_mfma_f32_16x16x32_bf16 v[116:119], v[180:183], v[204:207], v[116:119]
	v_mfma_f32_16x16x32_bf16 v[112:115], v[188:191], v[204:207], v[112:115]
	v_mfma_f32_16x16x32_bf16 v[108:111], v[180:183], v[212:215], v[108:111]
	v_mfma_f32_16x16x32_bf16 v[104:107], v[188:191], v[212:215], v[104:107]
	v_mfma_f32_16x16x32_bf16 v[100:103], v[180:183], v[220:223], v[100:103]
	v_mfma_f32_16x16x32_bf16 v[96:99], v[188:191], v[220:223], v[96:99]
	s_setprio 0
	s_barrier
	s_mov_b32 m0, s4
	ds_read_b128 v[132:135], v150
	ds_read_b128 v[224:227], v150 offset:1024
	ds_read_b128 v[228:231], v150 offset:256
	ds_read_b128 v[232:235], v150 offset:1280
	global_load_lds_dwordx4 v[136:137], off
	s_mov_b32 m0, s5
	v_lshl_add_u64 v[240:241], v[136:137], 0, s[8:9]
	global_load_lds_dwordx4 v[138:139], off
	v_lshl_add_u64 v[242:243], v[138:139], 0, s[8:9]
	s_barrier
	s_waitcnt lgkmcnt(0)
	s_setprio 1
	s_waitcnt lgkmcnt(0)
	v_mfma_f32_16x16x32_bf16 v[84:87], v[132:135], v[192:195], v[84:87]
	v_mfma_f32_16x16x32_bf16 v[68:71], v[228:231], v[192:195], v[68:71]
	v_mfma_f32_16x16x32_bf16 v[52:55], v[132:135], v[200:203], v[52:55]
	v_mfma_f32_16x16x32_bf16 v[48:51], v[228:231], v[200:203], v[48:51]
	v_mfma_f32_16x16x32_bf16 v[44:47], v[132:135], v[208:211], v[44:47]
	v_mfma_f32_16x16x32_bf16 v[40:43], v[228:231], v[208:211], v[40:43]
	v_mfma_f32_16x16x32_bf16 v[36:39], v[132:135], v[216:219], v[36:39]
	v_mfma_f32_16x16x32_bf16 v[32:35], v[228:231], v[216:219], v[32:35]
	v_mfma_f32_16x16x32_bf16 v[84:87], v[224:227], v[196:199], v[84:87]
	v_mfma_f32_16x16x32_bf16 v[68:71], v[232:235], v[196:199], v[68:71]
	v_mfma_f32_16x16x32_bf16 v[52:55], v[224:227], v[204:207], v[52:55]
	v_mfma_f32_16x16x32_bf16 v[48:51], v[232:235], v[204:207], v[48:51]
	v_mfma_f32_16x16x32_bf16 v[44:47], v[224:227], v[212:215], v[44:47]
	v_mfma_f32_16x16x32_bf16 v[40:43], v[232:235], v[212:215], v[40:43]
	v_mfma_f32_16x16x32_bf16 v[36:39], v[224:227], v[220:223], v[36:39]
	v_mfma_f32_16x16x32_bf16 v[32:35], v[232:235], v[220:223], v[32:35]
	s_setprio 0
	s_mov_b32 m0, s1
	s_barrier
	ds_read_b128 v[136:139], v128 offset:16384
	ds_read_b128 v[192:195], v128 offset:17408
	ds_read_b128 v[196:199], v153 offset:16384
	ds_read_b128 v[200:203], v153 offset:17408
	ds_read_b128 v[204:207], v154 offset:16384
	ds_read_b128 v[208:211], v154 offset:17408
	ds_read_b128 v[212:215], v155 offset:16384
	ds_read_b128 v[216:219], v155 offset:17408
	global_load_lds_dwordx4 v[140:141], off
	s_mov_b32 m0, s6
	v_lshl_add_u64 v[244:245], v[140:141], 0, s[8:9]
	global_load_lds_dwordx4 v[142:143], off
	v_lshl_add_u64 v[246:247], v[142:143], 0, s[8:9]
	s_barrier
	s_waitcnt lgkmcnt(0)
	s_setprio 1
	s_waitcnt lgkmcnt(0)
	v_mfma_f32_16x16x32_bf16 v[28:31], v[156:159], v[136:139], v[28:31]
	v_mfma_f32_16x16x32_bf16 v[24:27], v[184:187], v[136:139], v[24:27]
	v_mfma_f32_16x16x32_bf16 v[20:23], v[156:159], v[196:199], v[20:23]
	v_mfma_f32_16x16x32_bf16 v[16:19], v[184:187], v[196:199], v[16:19]
	v_mfma_f32_16x16x32_bf16 v[12:15], v[156:159], v[204:207], v[12:15]
	v_mfma_f32_16x16x32_bf16 v[8:11], v[184:187], v[204:207], v[8:11]
	v_mfma_f32_16x16x32_bf16 v[4:7], v[156:159], v[212:215], v[4:7]
	v_mfma_f32_16x16x32_bf16 v[0:3], v[184:187], v[212:215], v[0:3]
	v_mfma_f32_16x16x32_bf16 v[28:31], v[180:183], v[192:195], v[28:31]
	v_mfma_f32_16x16x32_bf16 v[24:27], v[188:191], v[192:195], v[24:27]
	v_mfma_f32_16x16x32_bf16 v[20:23], v[180:183], v[200:203], v[20:23]
	v_mfma_f32_16x16x32_bf16 v[16:19], v[188:191], v[200:203], v[16:19]
	v_mfma_f32_16x16x32_bf16 v[12:15], v[180:183], v[208:211], v[12:15]
	v_mfma_f32_16x16x32_bf16 v[8:11], v[188:191], v[208:211], v[8:11]
	v_mfma_f32_16x16x32_bf16 v[4:7], v[180:183], v[216:219], v[4:7]
	v_mfma_f32_16x16x32_bf16 v[0:3], v[188:191], v[216:219], v[0:3]
	s_setprio 0
	s_barrier
	s_mov_b32 m0, s7
	v_lshl_add_u64 v[248:249], v[144:145], 0, s[8:9]
	global_load_lds_dwordx4 v[144:145], off
	s_mov_b32 m0, s35
	v_lshl_add_u64 v[250:251], v[146:147], 0, s[8:9]
	global_load_lds_dwordx4 v[146:147], off
	s_waitcnt vmcnt(6)
	s_barrier
	s_setprio 1
	v_mfma_f32_16x16x32_bf16 v[56:59], v[132:135], v[136:139], v[56:59]
	v_mfma_f32_16x16x32_bf16 v[60:63], v[228:231], v[136:139], v[60:63]
	v_mfma_f32_16x16x32_bf16 v[64:67], v[132:135], v[196:199], v[64:67]
	v_mfma_f32_16x16x32_bf16 v[72:75], v[228:231], v[196:199], v[72:75]
	v_mfma_f32_16x16x32_bf16 v[76:79], v[132:135], v[204:207], v[76:79]
	v_mfma_f32_16x16x32_bf16 v[80:83], v[228:231], v[204:207], v[80:83]
	v_mfma_f32_16x16x32_bf16 v[88:91], v[132:135], v[212:215], v[88:91]
	v_mfma_f32_16x16x32_bf16 v[92:95], v[228:231], v[212:215], v[92:95]
	v_mfma_f32_16x16x32_bf16 v[56:59], v[224:227], v[192:195], v[56:59]
	v_mfma_f32_16x16x32_bf16 v[60:63], v[232:235], v[192:195], v[60:63]
	v_mfma_f32_16x16x32_bf16 v[64:67], v[224:227], v[200:203], v[64:67]
	v_mfma_f32_16x16x32_bf16 v[72:75], v[232:235], v[200:203], v[72:75]
	v_mfma_f32_16x16x32_bf16 v[76:79], v[224:227], v[208:211], v[76:79]
	v_mfma_f32_16x16x32_bf16 v[80:83], v[232:235], v[208:211], v[80:83]
	v_mfma_f32_16x16x32_bf16 v[88:91], v[224:227], v[216:219], v[88:91]
	v_mfma_f32_16x16x32_bf16 v[92:95], v[232:235], v[216:219], v[92:95]
	s_setprio 0
	s_barrier
; #define STAGE(P, q) do { GLDS16(q[0], (unsigned char*)(P) + wid * 1024); GLDS16(q[1], (unsigned char*)(P) + wid * 1024 + 8192); \
;     q[0] += 128; q[1] += 128; asm volatile("" : "+v"(q[0]), "+v"(q[1])); } while (0)
; #define LDA(dst, b, h) _Pragma("unroll") for (int m = 0; m < 4; ++m) _Pragma("unroll") for (int k = 0; k < 2; ++k) \
;     dst[m][k] = *(const bf16x8*)((const unsigned char*)SA(b, h) + lds_byte1(wr * 64 + m * 16 + fr, k * 32 + fq * 8))
; #define LDB(dst, b, h) _Pragma("unroll") for (int n = 0; n < 2; ++n) _Pragma("unroll") for (int k = 0; k < 2; ++k) \
;     dst[n][k] = *(const bf16x8*)((const unsigned char*)SB(b, h) + lds_byte1(wc * 32 + n * 16 + fr, k * 32 + fq * 8))
; #define MMA(ai, bj, At_, Bt_) do { __builtin_amdgcn_s_setprio(1); \
;     _Pragma("unroll") for (int m = 0; m < 4; ++m) _Pragma("unroll") for (int n = 0; n < 2; ++n) _Pragma("unroll") for (int k = 0; k < 2; ++k) \
;       acc[ai][bj][m][n] = mfma16(At_[m][k], Bt_[n][k], acc[ai][bj][m][n]); \
;     __builtin_amdgcn_s_setprio(0); } while (0)
; #define WAIT_V(n) asm volatile("s_waitcnt vmcnt(" #n ")" ::: "memory")
; #define WAIT_L(n) asm volatile("s_waitcnt lgkmcnt(" #n ")" ::: "memory")
; #define BAR __builtin_amdgcn_s_barrier()
; DEV void gemm_tile(const u16* __restrict__ A, const u16* __restrict__ Bt, u16* __restrict__ C, int N, int K,
;                    int brow, int bcol, unsigned char* smem, int epi, const GateEpi& ge) {
;     ...
;   STAGE(SB(0, 0), qB0); STAGE(SA(0, 0), qA0);
;   STAGE(SB(0, 1), qB1); STAGE(SA(0, 1), qA1);
;   if (wr == 1) BAR;
;   WAIT_V(4); BAR;
;   STAGE(SB(1, 0), qB0); STAGE(SA(1, 0), qA0); STAGE(SB(1, 1), qB1);
;     ...
;     LDB(B1, 0, 1); BAR; WAIT_L(0); MMA(0, 1, At, B1); BAR;
;     LDA(At, 0, 1); WAIT_V(4); BAR; WAIT_L(0); MMA(1, 0, At, B0); MMA(1, 1, At, B1); BAR; }
;   { LDB(B0, 1, 0); LDA(At, 1, 0); WAIT_V(2); BAR; WAIT_L(0); MMA(0, 0, At, B0); BAR;
;     LDB(B1, 1, 1); WAIT_V(0); BAR; WAIT_L(0); MMA(0, 1, At, B1); BAR;
;     LDA(At, 1, 1); BAR; WAIT_L(0); MMA(1, 0, At, B0); MMA(1, 1, At, B1); BAR; }
	ds_read_b128 v[144:147], v149
	ds_read_b128 v[156:159], v149 offset:1024
	ds_read_b128 v[180:183], v149 offset:256
	ds_read_b128 v[184:187], v149 offset:1280
	s_mov_b32 m0, s41
	ds_read_b128 v[140:143], v128 offset:32768
	ds_read_b128 v[188:191], v128 offset:33792
	ds_read_b128 v[192:195], v153 offset:32768
	ds_read_b128 v[196:199], v153 offset:33792
	ds_read_b128 v[200:203], v154 offset:32768
	ds_read_b128 v[204:207], v154 offset:33792
	ds_read_b128 v[208:211], v155 offset:32768
	ds_read_b128 v[212:215], v155 offset:33792
	global_load_lds_dwordx4 v[236:237], off
	s_mov_b32 m0, vcc_lo
	v_lshl_add_u64 v[132:133], v[236:237], 0, s[8:9]
	global_load_lds_dwordx4 v[238:239], off
	v_lshl_add_u64 v[134:135], v[238:239], 0, s[8:9]
	s_waitcnt lgkmcnt(8)
	s_barrier
	s_waitcnt lgkmcnt(0)
	s_setprio 1
	s_waitcnt lgkmcnt(0)
	v_mfma_f32_16x16x32_bf16 v[124:127], v[144:147], v[140:143], v[124:127]
	v_mfma_f32_16x16x32_bf16 v[120:123], v[180:183], v[140:143], v[120:123]
	v_mfma_f32_16x16x32_bf16 v[116:119], v[144:147], v[192:195], v[116:119]
	v_mfma_f32_16x16x32_bf16 v[112:115], v[180:183], v[192:195], v[112:115]
	v_mfma_f32_16x16x32_bf16 v[108:111], v[144:147], v[200:203], v[108:111]
	v_mfma_f32_16x16x32_bf16 v[104:107], v[180:183], v[200:203], v[104:107]
	v_mfma_f32_16x16x32_bf16 v[100:103], v[144:147], v[208:211], v[100:103]
	v_mfma_f32_16x16x32_bf16 v[96:99], v[180:183], v[208:211], v[96:99]
	v_mfma_f32_16x16x32_bf16 v[124:127], v[156:159], v[188:191], v[124:127]
	v_mfma_f32_16x16x32_bf16 v[120:123], v[184:187], v[188:191], v[120:123]
	v_mfma_f32_16x16x32_bf16 v[116:119], v[156:159], v[196:199], v[116:119]
	v_mfma_f32_16x16x32_bf16 v[112:115], v[184:187], v[196:199], v[112:115]
	v_mfma_f32_16x16x32_bf16 v[108:111], v[156:159], v[204:207], v[108:111]
	v_mfma_f32_16x16x32_bf16 v[104:107], v[184:187], v[204:207], v[104:107]
	v_mfma_f32_16x16x32_bf16 v[100:103], v[156:159], v[212:215], v[100:103]
	v_mfma_f32_16x16x32_bf16 v[96:99], v[184:187], v[212:215], v[96:99]
	s_setprio 0
	s_barrier
	s_mov_b32 m0, vcc_hi
	ds_read_b128 v[216:219], v148
	ds_read_b128 v[220:223], v148 offset:1024
	ds_read_b128 v[224:227], v148 offset:256
	ds_read_b128 v[228:231], v148 offset:1280
	global_load_lds_dwordx4 v[240:241], off
	s_mov_b32 m0, s28
	v_lshl_add_u64 v[136:137], v[240:241], 0, s[8:9]
	global_load_lds_dwordx4 v[242:243], off
	v_lshl_add_u64 v[138:139], v[242:243], 0, s[8:9]
	s_barrier
	s_waitcnt lgkmcnt(0)
	s_setprio 1
	s_waitcnt lgkmcnt(0)
	v_mfma_f32_16x16x32_bf16 v[84:87], v[216:219], v[140:143], v[84:87]
	v_mfma_f32_16x16x32_bf16 v[68:71], v[224:227], v[140:143], v[68:71]
	v_mfma_f32_16x16x32_bf16 v[52:55], v[216:219], v[192:195], v[52:55]
	v_mfma_f32_16x16x32_bf16 v[48:51], v[224:227], v[192:195], v[48:51]
	v_mfma_f32_16x16x32_bf16 v[44:47], v[216:219], v[200:203], v[44:47]
	v_mfma_f32_16x16x32_bf16 v[40:43], v[224:227], v[200:203], v[40:43]
	v_mfma_f32_16x16x32_bf16 v[36:39], v[216:219], v[208:211], v[36:39]
	v_mfma_f32_16x16x32_bf16 v[32:35], v[224:227], v[208:211], v[32:35]
	v_mfma_f32_16x16x32_bf16 v[84:87], v[220:223], v[188:191], v[84:87]
	v_mfma_f32_16x16x32_bf16 v[68:71], v[228:231], v[188:191], v[68:71]
	v_mfma_f32_16x16x32_bf16 v[52:55], v[220:223], v[196:199], v[52:55]
	v_mfma_f32_16x16x32_bf16 v[48:51], v[228:231], v[196:199], v[48:51]
	v_mfma_f32_16x16x32_bf16 v[44:47], v[220:223], v[204:207], v[44:47]
	v_mfma_f32_16x16x32_bf16 v[40:43], v[228:231], v[204:207], v[40:43]
	v_mfma_f32_16x16x32_bf16 v[36:39], v[220:223], v[212:215], v[36:39]
	v_mfma_f32_16x16x32_bf16 v[32:35], v[228:231], v[212:215], v[32:35]
	s_setprio 0
	s_mov_b32 m0, s94
	s_barrier
	ds_read_b128 v[188:191], v128 offset:49152
	ds_read_b128 v[192:195], v128 offset:50176
	ds_read_b128 v[196:199], v153 offset:49152
	ds_read_b128 v[200:203], v153 offset:50176
	ds_read_b128 v[204:207], v154 offset:49152
	ds_read_b128 v[208:211], v154 offset:50176
	ds_read_b128 v[212:215], v155 offset:49152
	ds_read_b128 v[232:235], v155 offset:50176
	global_load_lds_dwordx4 v[244:245], off
	s_mov_b32 m0, s95
	v_lshl_add_u64 v[140:141], v[244:245], 0, s[8:9]
	global_load_lds_dwordx4 v[246:247], off
	v_lshl_add_u64 v[142:143], v[246:247], 0, s[8:9]
	s_barrier
	s_waitcnt lgkmcnt(0)
	s_setprio 1
	s_waitcnt lgkmcnt(0)
	v_mfma_f32_16x16x32_bf16 v[28:31], v[144:147], v[188:191], v[28:31]
	v_mfma_f32_16x16x32_bf16 v[24:27], v[180:183], v[188:191], v[24:27]
	v_mfma_f32_16x16x32_bf16 v[20:23], v[144:147], v[196:199], v[20:23]
	v_mfma_f32_16x16x32_bf16 v[16:19], v[180:183], v[196:199], v[16:19]
	v_mfma_f32_16x16x32_bf16 v[12:15], v[144:147], v[204:207], v[12:15]
	v_mfma_f32_16x16x32_bf16 v[8:11], v[180:183], v[204:207], v[8:11]
	v_mfma_f32_16x16x32_bf16 v[4:7], v[144:147], v[212:215], v[4:7]
	v_mfma_f32_16x16x32_bf16 v[0:3], v[180:183], v[212:215], v[0:3]
	v_mfma_f32_16x16x32_bf16 v[28:31], v[156:159], v[192:195], v[28:31]
	v_mfma_f32_16x16x32_bf16 v[24:27], v[184:187], v[192:195], v[24:27]
	v_mfma_f32_16x16x32_bf16 v[20:23], v[156:159], v[200:203], v[20:23]
	v_mfma_f32_16x16x32_bf16 v[16:19], v[184:187], v[200:203], v[16:19]
	v_mfma_f32_16x16x32_bf16 v[12:15], v[156:159], v[208:211], v[12:15]
	v_mfma_f32_16x16x32_bf16 v[8:11], v[184:187], v[208:211], v[8:11]
	v_mfma_f32_16x16x32_bf16 v[4:7], v[156:159], v[232:235], v[4:7]
	v_mfma_f32_16x16x32_bf16 v[0:3], v[184:187], v[232:235], v[0:3]
	s_setprio 0
	s_barrier
	s_mov_b32 m0, s62
	v_lshl_add_u64 v[144:145], v[248:249], 0, s[8:9]
	global_load_lds_dwordx4 v[248:249], off
	s_mov_b32 m0, s63
	v_lshl_add_u64 v[146:147], v[250:251], 0, s[8:9]
	global_load_lds_dwordx4 v[250:251], off
	s_waitcnt vmcnt(6)
	s_barrier
	s_setprio 1
	v_mfma_f32_16x16x32_bf16 v[56:59], v[216:219], v[188:191], v[56:59]
	v_mfma_f32_16x16x32_bf16 v[60:63], v[224:227], v[188:191], v[60:63]
	v_mfma_f32_16x16x32_bf16 v[64:67], v[216:219], v[196:199], v[64:67]
	v_mfma_f32_16x16x32_bf16 v[72:75], v[224:227], v[196:199], v[72:75]
	v_mfma_f32_16x16x32_bf16 v[76:79], v[216:219], v[204:207], v[76:79]
	v_mfma_f32_16x16x32_bf16 v[80:83], v[224:227], v[204:207], v[80:83]
	v_mfma_f32_16x16x32_bf16 v[88:91], v[216:219], v[212:215], v[88:91]
	v_mfma_f32_16x16x32_bf16 v[92:95], v[224:227], v[212:215], v[92:95]
	v_mfma_f32_16x16x32_bf16 v[56:59], v[220:223], v[192:195], v[56:59]
	v_mfma_f32_16x16x32_bf16 v[60:63], v[228:231], v[192:195], v[60:63]
	v_mfma_f32_16x16x32_bf16 v[64:67], v[220:223], v[200:203], v[64:67]
	v_mfma_f32_16x16x32_bf16 v[72:75], v[228:231], v[200:203], v[72:75]
	v_mfma_f32_16x16x32_bf16 v[76:79], v[220:223], v[208:211], v[76:79]
	v_mfma_f32_16x16x32_bf16 v[80:83], v[228:231], v[208:211], v[80:83]
	v_mfma_f32_16x16x32_bf16 v[88:91], v[220:223], v[232:235], v[88:91]
	v_mfma_f32_16x16x32_bf16 v[92:95], v[228:231], v[232:235], v[92:95]
	s_setprio 0
	s_barrier
	s_mov_b32 m0, s56
	s_nop 0
	global_load_lds_dwordx4 v[132:133], off
	s_mov_b32 m0, s52
	s_nop 0
	global_load_lds_dwordx4 v[134:135], off
	s_mov_b32 s63, 1

; #define STAGE(P, q) do { GLDS16(q[0], (unsigned char*)(P) + wid * 1024); GLDS16(q[1], (unsigned char*)(P) + wid * 1024 + 8192); \
;     q[0] += 128; q[1] += 128; asm volatile("" : "+v"(q[0]), "+v"(q[1])); } while (0)
; #define LDA(dst, b, h) _Pragma("unroll") for (int m = 0; m < 4; ++m) _Pragma("unroll") for (int k = 0; k < 2; ++k) \
;     dst[m][k] = *(const bf16x8*)((const unsigned char*)SA(b, h) + lds_byte1(wr * 64 + m * 16 + fr, k * 32 + fq * 8))
; #define LDB(dst, b, h) _Pragma("unroll") for (int n = 0; n < 2; ++n) _Pragma("unroll") for (int k = 0; k < 2; ++k) \
;     dst[n][k] = *(const bf16x8*)((const unsigned char*)SB(b, h) + lds_byte1(wc * 32 + n * 16 + fr, k * 32 + fq * 8))
; #define MMA(ai, bj, At_, Bt_) do { __builtin_amdgcn_s_setprio(1); \
;     _Pragma("unroll") for (int m = 0; m < 4; ++m) _Pragma("unroll") for (int n = 0; n < 2; ++n) _Pragma("unroll") for (int k = 0; k < 2; ++k) \
;       acc[ai][bj][m][n] = mfma16(At_[m][k], Bt_[n][k], acc[ai][bj][m][n]); \
;     __builtin_amdgcn_s_setprio(0); } while (0)
; #define WAIT_V(n) asm volatile("s_waitcnt vmcnt(" #n ")" ::: "memory")
; #define WAIT_L(n) asm volatile("s_waitcnt lgkmcnt(" #n ")" ::: "memory")
; #define BAR __builtin_amdgcn_s_barrier()
; #define SCHED __builtin_amdgcn_sched_barrier(0)
; DEV void gemm_tile(const u16* __restrict__ A, const u16* __restrict__ Bt, u16* __restrict__ C, int N, int K,
;                    int brow, int bcol, unsigned char* smem, int epi, const GateEpi& ge) {
;     ...
;   for (int t = 0; t < nt - 2; t += 2) {
;     LDB(B0, 0, 0); SCHED; LDA(At, 0, 0); STAGE(SA(1, 1), qA1);
;     WAIT_L(8); BAR; WAIT_L(0); MMA(0, 0, At, B0); BAR; SCHED;
;     LDB(B1, 0, 1); STAGE(SB(0, 0), qB0);
;     BAR; WAIT_L(0); MMA(0, 1, At, B1); BAR;
;     LDA(At, 0, 1); STAGE(SA(0, 0), qA0);
;     BAR; WAIT_L(0); MMA(1, 0, At, B0); BAR; SCHED;
;     STAGE(SB(0, 1), qB1);
;     WAIT_V(6); BAR; MMA(1, 1, At, B1); BAR;
.Lg_nostag:
	ds_read_b128 v[156:159], v152
	ds_read_b128 v[180:183], v152 offset:1024
	ds_read_b128 v[184:187], v152 offset:256
	ds_read_b128 v[188:191], v152 offset:1280
	s_mov_b32 m0, s56
	v_add_u32_e32 v153, s53, v151
	v_add_u32_e32 v154, s54, v151
	v_add_u32_e32 v155, s55, v151
	ds_read_b128 v[192:195], v128
	ds_read_b128 v[196:199], v128 offset:1024
	ds_read_b128 v[200:203], v153
	ds_read_b128 v[204:207], v153 offset:1024
	ds_read_b128 v[208:211], v154
	ds_read_b128 v[212:215], v154 offset:1024
	ds_read_b128 v[216:219], v155
	ds_read_b128 v[220:223], v155 offset:1024
	s_mov_b32 m0, s52
	v_lshl_add_u64 v[236:237], v[132:133], 0, s[8:9]
	v_lshl_add_u64 v[238:239], v[134:135], 0, s[8:9]
	s_waitcnt lgkmcnt(8)
	s_barrier
	s_waitcnt lgkmcnt(0)
	s_setprio 1
	s_waitcnt lgkmcnt(0)
	v_mfma_f32_16x16x32_bf16 v[124:127], v[156:159], v[192:195], 0
	v_mfma_f32_16x16x32_bf16 v[120:123], v[184:187], v[192:195], 0
	v_mfma_f32_16x16x32_bf16 v[116:119], v[156:159], v[200:203], 0
	v_mfma_f32_16x16x32_bf16 v[112:115], v[184:187], v[200:203], 0
	v_mfma_f32_16x16x32_bf16 v[108:111], v[156:159], v[208:211], 0
	v_mfma_f32_16x16x32_bf16 v[104:107], v[184:187], v[208:211], 0
	v_mfma_f32_16x16x32_bf16 v[100:103], v[156:159], v[216:219], 0
	v_mfma_f32_16x16x32_bf16 v[96:99], v[184:187], v[216:219], 0
	v_mfma_f32_16x16x32_bf16 v[124:127], v[180:183], v[196:199], v[124:127]
	v_mfma_f32_16x16x32_bf16 v[120:123], v[188:191], v[196:199], v[120:123]
	v_mfma_f32_16x16x32_bf16 v[116:119], v[180:183], v[204:207], v[116:119]
	v_mfma_f32_16x16x32_bf16 v[112:115], v[188:191], v[204:207], v[112:115]
	v_mfma_f32_16x16x32_bf16 v[108:111], v[180:183], v[212:215], v[108:111]
	v_mfma_f32_16x16x32_bf16 v[104:107], v[188:191], v[212:215], v[104:107]
	v_mfma_f32_16x16x32_bf16 v[100:103], v[180:183], v[220:223], v[100:103]
	v_mfma_f32_16x16x32_bf16 v[96:99], v[188:191], v[220:223], v[96:99]
	s_setprio 0
	s_barrier
	s_mov_b32 m0, s4
	ds_read_b128 v[132:135], v150
	ds_read_b128 v[224:227], v150 offset:1024
	ds_read_b128 v[228:231], v150 offset:256
	ds_read_b128 v[232:235], v150 offset:1280
	global_load_lds_dwordx4 v[136:137], off
	s_mov_b32 m0, s5
	v_lshl_add_u64 v[240:241], v[136:137], 0, s[8:9]
	global_load_lds_dwordx4 v[138:139], off
	v_lshl_add_u64 v[242:243], v[138:139], 0, s[8:9]
	s_barrier
	s_waitcnt lgkmcnt(0)
	s_setprio 1
	s_waitcnt lgkmcnt(0)
	v_mfma_f32_16x16x32_bf16 v[84:87], v[132:135], v[192:195], 0
	v_mfma_f32_16x16x32_bf16 v[68:71], v[228:231], v[192:195], 0
	v_mfma_f32_16x16x32_bf16 v[52:55], v[132:135], v[200:203], 0
	v_mfma_f32_16x16x32_bf16 v[48:51], v[228:231], v[200:203], 0
	v_mfma_f32_16x16x32_bf16 v[44:47], v[132:135], v[208:211], 0
	v_mfma_f32_16x16x32_bf16 v[40:43], v[228:231], v[208:211], 0
	v_mfma_f32_16x16x32_bf16 v[36:39], v[132:135], v[216:219], 0
	v_mfma_f32_16x16x32_bf16 v[32:35], v[228:231], v[216:219], 0
	v_mfma_f32_16x16x32_bf16 v[84:87], v[224:227], v[196:199], v[84:87]
	v_mfma_f32_16x16x32_bf16 v[68:71], v[232:235], v[196:199], v[68:71]
	v_mfma_f32_16x16x32_bf16 v[52:55], v[224:227], v[204:207], v[52:55]
	v_mfma_f32_16x16x32_bf16 v[48:51], v[232:235], v[204:207], v[48:51]
	v_mfma_f32_16x16x32_bf16 v[44:47], v[224:227], v[212:215], v[44:47]
	v_mfma_f32_16x16x32_bf16 v[40:43], v[232:235], v[212:215], v[40:43]
	v_mfma_f32_16x16x32_bf16 v[36:39], v[224:227], v[220:223], v[36:39]
	v_mfma_f32_16x16x32_bf16 v[32:35], v[232:235], v[220:223], v[32:35]
	s_setprio 0
	s_mov_b32 m0, s1
	s_barrier
	ds_read_b128 v[136:139], v128 offset:16384
	ds_read_b128 v[192:195], v128 offset:17408
	ds_read_b128 v[196:199], v153 offset:16384
	ds_read_b128 v[200:203], v153 offset:17408
	ds_read_b128 v[204:207], v154 offset:16384
	ds_read_b128 v[208:211], v154 offset:17408
	ds_read_b128 v[212:215], v155 offset:16384
	ds_read_b128 v[216:219], v155 offset:17408
	global_load_lds_dwordx4 v[140:141], off
	s_mov_b32 m0, s6
	v_lshl_add_u64 v[244:245], v[140:141], 0, s[8:9]
	global_load_lds_dwordx4 v[142:143], off
	v_lshl_add_u64 v[246:247], v[142:143], 0, s[8:9]
	s_barrier
	s_waitcnt lgkmcnt(0)
	s_setprio 1
	s_waitcnt lgkmcnt(0)
	v_mfma_f32_16x16x32_bf16 v[28:31], v[156:159], v[136:139], 0
	v_mfma_f32_16x16x32_bf16 v[24:27], v[184:187], v[136:139], 0
	v_mfma_f32_16x16x32_bf16 v[20:23], v[156:159], v[196:199], 0
	v_mfma_f32_16x16x32_bf16 v[16:19], v[184:187], v[196:199], 0
	v_mfma_f32_16x16x32_bf16 v[12:15], v[156:159], v[204:207], 0
	v_mfma_f32_16x16x32_bf16 v[8:11], v[184:187], v[204:207], 0
	v_mfma_f32_16x16x32_bf16 v[4:7], v[156:159], v[212:215], 0
	v_mfma_f32_16x16x32_bf16 v[0:3], v[184:187], v[212:215], 0
	v_mfma_f32_16x16x32_bf16 v[28:31], v[180:183], v[192:195], v[28:31]
	v_mfma_f32_16x16x32_bf16 v[24:27], v[188:191], v[192:195], v[24:27]
	v_mfma_f32_16x16x32_bf16 v[20:23], v[180:183], v[200:203], v[20:23]
	v_mfma_f32_16x16x32_bf16 v[16:19], v[188:191], v[200:203], v[16:19]
	v_mfma_f32_16x16x32_bf16 v[12:15], v[180:183], v[208:211], v[12:15]
	v_mfma_f32_16x16x32_bf16 v[8:11], v[188:191], v[208:211], v[8:11]
	v_mfma_f32_16x16x32_bf16 v[4:7], v[180:183], v[216:219], v[4:7]
	v_mfma_f32_16x16x32_bf16 v[0:3], v[188:191], v[216:219], v[0:3]
	s_setprio 0
	s_barrier
	s_mov_b32 m0, s7
	v_lshl_add_u64 v[248:249], v[144:145], 0, s[8:9]
	global_load_lds_dwordx4 v[144:145], off
	s_mov_b32 m0, s35
	v_lshl_add_u64 v[250:251], v[146:147], 0, s[8:9]
	global_load_lds_dwordx4 v[146:147], off
	s_andn2_b64 s[58:59], exec, s[2:3]
	s_cmp_lg_u64 s[58:59], 0
	s_cbranch_scc1 .Lf_plainw
	s_waitcnt vmcnt(14)
	s_branch .Lf_wdone
.Lf_plainw:
	s_waitcnt vmcnt(22)
; #define STAGE(P, q) do { GLDS16(q[0], (unsigned char*)(P) + wid * 1024); GLDS16(q[1], (unsigned char*)(P) + wid * 1024 + 8192); \
;     q[0] += 128; q[1] += 128; asm volatile("" : "+v"(q[0]), "+v"(q[1])); } while (0)
; #define LDA(dst, b, h) _Pragma("unroll") for (int m = 0; m < 4; ++m) _Pragma("unroll") for (int k = 0; k < 2; ++k) \
;     dst[m][k] = *(const bf16x8*)((const unsigned char*)SA(b, h) + lds_byte1(wr * 64 + m * 16 + fr, k * 32 + fq * 8))
; #define LDB(dst, b, h) _Pragma("unroll") for (int n = 0; n < 2; ++n) _Pragma("unroll") for (int k = 0; k < 2; ++k) \
;     dst[n][k] = *(const bf16x8*)((const unsigned char*)SB(b, h) + lds_byte1(wc * 32 + n * 16 + fr, k * 32 + fq * 8))
; #define MMA(ai, bj, At_, Bt_) do { __builtin_amdgcn_s_setprio(1); \
;     _Pragma("unroll") for (int m = 0; m < 4; ++m) _Pragma("unroll") for (int n = 0; n < 2; ++n) _Pragma("unroll") for (int k = 0; k < 2; ++k) \
;       acc[ai][bj][m][n] = mfma16(At_[m][k], Bt_[n][k], acc[ai][bj][m][n]); \
;     __builtin_amdgcn_s_setprio(0); } while (0)
; #define WAIT_V(n) asm volatile("s_waitcnt vmcnt(" #n ")" ::: "memory")
; #define WAIT_L(n) asm volatile("s_waitcnt lgkmcnt(" #n ")" ::: "memory")
; #define BAR __builtin_amdgcn_s_barrier()
; #define SCHED __builtin_amdgcn_sched_barrier(0)
; DEV void gemm_tile(const u16* __restrict__ A, const u16* __restrict__ Bt, u16* __restrict__ C, int N, int K,
;                    int brow, int bcol, unsigned char* smem, int epi, const GateEpi& ge) {
;     ...
;     WAIT_V(6); BAR; MMA(1, 1, At, B1); BAR;
;     LDB(B0, 1, 0); SCHED; LDA(At, 1, 0); STAGE(SA(0, 1), qA1);
;     WAIT_L(8); BAR; WAIT_L(0); MMA(0, 0, At, B0); BAR; SCHED;
;     LDB(B1, 1, 1); STAGE(SB(1, 0), qB0);
;     BAR; WAIT_L(0); MMA(0, 1, At, B1); BAR;
;     LDA(At, 1, 1); STAGE(SA(1, 0), qA0);
;     BAR; WAIT_L(0); MMA(1, 0, At, B0); BAR; SCHED;
.Lf_wdone:
	s_barrier
	s_setprio 1
	v_mfma_f32_16x16x32_bf16 v[56:59], v[132:135], v[136:139], 0
	v_mfma_f32_16x16x32_bf16 v[60:63], v[228:231], v[136:139], 0
	v_mfma_f32_16x16x32_bf16 v[64:67], v[132:135], v[196:199], 0
	v_mfma_f32_16x16x32_bf16 v[72:75], v[228:231], v[196:199], 0
	v_mfma_f32_16x16x32_bf16 v[76:79], v[132:135], v[204:207], 0
	v_mfma_f32_16x16x32_bf16 v[80:83], v[228:231], v[204:207], 0
	v_mfma_f32_16x16x32_bf16 v[88:91], v[132:135], v[212:215], 0
	v_mfma_f32_16x16x32_bf16 v[92:95], v[228:231], v[212:215], 0
	v_mfma_f32_16x16x32_bf16 v[56:59], v[224:227], v[192:195], v[56:59]
	v_mfma_f32_16x16x32_bf16 v[60:63], v[232:235], v[192:195], v[60:63]
	v_mfma_f32_16x16x32_bf16 v[64:67], v[224:227], v[200:203], v[64:67]
	v_mfma_f32_16x16x32_bf16 v[72:75], v[232:235], v[200:203], v[72:75]
	v_mfma_f32_16x16x32_bf16 v[76:79], v[224:227], v[208:211], v[76:79]
	v_mfma_f32_16x16x32_bf16 v[80:83], v[232:235], v[208:211], v[80:83]
	v_mfma_f32_16x16x32_bf16 v[88:91], v[224:227], v[216:219], v[88:91]
	v_mfma_f32_16x16x32_bf16 v[92:95], v[232:235], v[216:219], v[92:95]
	s_setprio 0
	s_barrier
	ds_read_b128 v[144:147], v149
	ds_read_b128 v[156:159], v149 offset:1024
	ds_read_b128 v[180:183], v149 offset:256
	ds_read_b128 v[184:187], v149 offset:1280
	s_mov_b32 m0, s41
	ds_read_b128 v[140:143], v128 offset:32768
	ds_read_b128 v[188:191], v128 offset:33792
	ds_read_b128 v[192:195], v153 offset:32768
	ds_read_b128 v[196:199], v153 offset:33792
	ds_read_b128 v[200:203], v154 offset:32768
	ds_read_b128 v[204:207], v154 offset:33792
	ds_read_b128 v[208:211], v155 offset:32768
	ds_read_b128 v[212:215], v155 offset:33792
	global_load_lds_dwordx4 v[236:237], off
	s_mov_b32 m0, vcc_lo
	v_lshl_add_u64 v[132:133], v[236:237], 0, s[8:9]
	global_load_lds_dwordx4 v[238:239], off
	v_lshl_add_u64 v[134:135], v[238:239], 0, s[8:9]
	s_waitcnt lgkmcnt(8)
	s_barrier
	s_waitcnt lgkmcnt(0)
	s_setprio 1
	s_waitcnt lgkmcnt(0)
	v_mfma_f32_16x16x32_bf16 v[124:127], v[144:147], v[140:143], v[124:127]
	v_mfma_f32_16x16x32_bf16 v[120:123], v[180:183], v[140:143], v[120:123]
	v_mfma_f32_16x16x32_bf16 v[116:119], v[144:147], v[192:195], v[116:119]
	v_mfma_f32_16x16x32_bf16 v[112:115], v[180:183], v[192:195], v[112:115]
	v_mfma_f32_16x16x32_bf16 v[108:111], v[144:147], v[200:203], v[108:111]
	v_mfma_f32_16x16x32_bf16 v[104:107], v[180:183], v[200:203], v[104:107]
	v_mfma_f32_16x16x32_bf16 v[100:103], v[144:147], v[208:211], v[100:103]
	v_mfma_f32_16x16x32_bf16 v[96:99], v[180:183], v[208:211], v[96:99]
	v_mfma_f32_16x16x32_bf16 v[124:127], v[156:159], v[188:191], v[124:127]
	v_mfma_f32_16x16x32_bf16 v[120:123], v[184:187], v[188:191], v[120:123]
	v_mfma_f32_16x16x32_bf16 v[116:119], v[156:159], v[196:199], v[116:119]
	v_mfma_f32_16x16x32_bf16 v[112:115], v[184:187], v[196:199], v[112:115]
	v_mfma_f32_16x16x32_bf16 v[108:111], v[156:159], v[204:207], v[108:111]
	v_mfma_f32_16x16x32_bf16 v[104:107], v[184:187], v[204:207], v[104:107]
	v_mfma_f32_16x16x32_bf16 v[100:103], v[156:159], v[212:215], v[100:103]
	v_mfma_f32_16x16x32_bf16 v[96:99], v[184:187], v[212:215], v[96:99]
	s_setprio 0
	s_barrier
	s_mov_b32 m0, vcc_hi
	ds_read_b128 v[216:219], v148
	ds_read_b128 v[220:223], v148 offset:1024
	ds_read_b128 v[224:227], v148 offset:256
	ds_read_b128 v[228:231], v148 offset:1280
	global_load_lds_dwordx4 v[240:241], off
	s_mov_b32 m0, s28
	v_lshl_add_u64 v[136:137], v[240:241], 0, s[8:9]
	global_load_lds_dwordx4 v[242:243], off
	v_lshl_add_u64 v[138:139], v[242:243], 0, s[8:9]
	s_barrier
; #define STAGE(P, q) do { GLDS16(q[0], (unsigned char*)(P) + wid * 1024); GLDS16(q[1], (unsigned char*)(P) + wid * 1024 + 8192); \
;     q[0] += 128; q[1] += 128; asm volatile("" : "+v"(q[0]), "+v"(q[1])); } while (0)
; #define MMA(ai, bj, At_, Bt_) do { __builtin_amdgcn_s_setprio(1); \
;     _Pragma("unroll") for (int m = 0; m < 4; ++m) _Pragma("unroll") for (int n = 0; n < 2; ++n) _Pragma("unroll") for (int k = 0; k < 2; ++k) \
;       acc[ai][bj][m][n] = mfma16(At_[m][k], Bt_[n][k], acc[ai][bj][m][n]); \
;     __builtin_amdgcn_s_setprio(0); } while (0)
; #define WAIT_V(n) asm volatile("s_waitcnt vmcnt(" #n ")" ::: "memory")
; #define WAIT_L(n) asm volatile("s_waitcnt lgkmcnt(" #n ")" ::: "memory")
; #define BAR __builtin_amdgcn_s_barrier()
; #define SCHED __builtin_amdgcn_sched_barrier(0)
; DEV void gemm_tile(const u16* __restrict__ A, const u16* __restrict__ Bt, u16* __restrict__ C, int N, int K,
;                    int brow, int bcol, unsigned char* smem, int epi, const GateEpi& ge) {
;     ...
;     BAR; WAIT_L(0); MMA(1, 0, At, B0); BAR; SCHED;
;     STAGE(SB(1, 1), qB1);
;     WAIT_V(6); BAR; MMA(1, 1, At, B1); BAR;
	s_waitcnt lgkmcnt(0)
	s_setprio 1
	s_waitcnt lgkmcnt(0)
	v_mfma_f32_16x16x32_bf16 v[84:87], v[216:219], v[140:143], v[84:87]
	v_mfma_f32_16x16x32_bf16 v[68:71], v[224:227], v[140:143], v[68:71]
	v_mfma_f32_16x16x32_bf16 v[52:55], v[216:219], v[192:195], v[52:55]
	v_mfma_f32_16x16x32_bf16 v[48:51], v[224:227], v[192:195], v[48:51]
	v_mfma_f32_16x16x32_bf16 v[44:47], v[216:219], v[200:203], v[44:47]
	v_mfma_f32_16x16x32_bf16 v[40:43], v[224:227], v[200:203], v[40:43]
	v_mfma_f32_16x16x32_bf16 v[36:39], v[216:219], v[208:211], v[36:39]
	v_mfma_f32_16x16x32_bf16 v[32:35], v[224:227], v[208:211], v[32:35]
	v_mfma_f32_16x16x32_bf16 v[84:87], v[220:223], v[188:191], v[84:87]
	v_mfma_f32_16x16x32_bf16 v[68:71], v[228:231], v[188:191], v[68:71]
	v_mfma_f32_16x16x32_bf16 v[52:55], v[220:223], v[196:199], v[52:55]
	v_mfma_f32_16x16x32_bf16 v[48:51], v[228:231], v[196:199], v[48:51]
	v_mfma_f32_16x16x32_bf16 v[44:47], v[220:223], v[204:207], v[44:47]
	v_mfma_f32_16x16x32_bf16 v[40:43], v[228:231], v[204:207], v[40:43]
	v_mfma_f32_16x16x32_bf16 v[36:39], v[220:223], v[212:215], v[36:39]
	v_mfma_f32_16x16x32_bf16 v[32:35], v[228:231], v[212:215], v[32:35]
	s_setprio 0
	s_mov_b32 m0, s94
	s_barrier
	ds_read_b128 v[188:191], v128 offset:49152
	ds_read_b128 v[192:195], v128 offset:50176
	ds_read_b128 v[196:199], v153 offset:49152
	ds_read_b128 v[200:203], v153 offset:50176
	ds_read_b128 v[204:207], v154 offset:49152
	ds_read_b128 v[208:211], v154 offset:50176
	ds_read_b128 v[212:215], v155 offset:49152
	ds_read_b128 v[232:235], v155 offset:50176
	global_load_lds_dwordx4 v[244:245], off
	s_mov_b32 m0, s95
	v_lshl_add_u64 v[140:141], v[244:245], 0, s[8:9]
	global_load_lds_dwordx4 v[246:247], off
	v_lshl_add_u64 v[142:143], v[246:247], 0, s[8:9]
	s_barrier
	s_waitcnt lgkmcnt(0)
	s_setprio 1
	s_waitcnt lgkmcnt(0)
	v_mfma_f32_16x16x32_bf16 v[28:31], v[144:147], v[188:191], v[28:31]
	v_mfma_f32_16x16x32_bf16 v[24:27], v[180:183], v[188:191], v[24:27]
	v_mfma_f32_16x16x32_bf16 v[20:23], v[144:147], v[196:199], v[20:23]
	v_mfma_f32_16x16x32_bf16 v[16:19], v[180:183], v[196:199], v[16:19]
	v_mfma_f32_16x16x32_bf16 v[12:15], v[144:147], v[204:207], v[12:15]
	v_mfma_f32_16x16x32_bf16 v[8:11], v[180:183], v[204:207], v[8:11]
	v_mfma_f32_16x16x32_bf16 v[4:7], v[144:147], v[212:215], v[4:7]
	v_mfma_f32_16x16x32_bf16 v[0:3], v[180:183], v[212:215], v[0:3]
	v_mfma_f32_16x16x32_bf16 v[28:31], v[156:159], v[192:195], v[28:31]
	v_mfma_f32_16x16x32_bf16 v[24:27], v[184:187], v[192:195], v[24:27]
	v_mfma_f32_16x16x32_bf16 v[20:23], v[156:159], v[200:203], v[20:23]
	v_mfma_f32_16x16x32_bf16 v[16:19], v[184:187], v[200:203], v[16:19]
	v_mfma_f32_16x16x32_bf16 v[12:15], v[156:159], v[208:211], v[12:15]
	v_mfma_f32_16x16x32_bf16 v[8:11], v[184:187], v[208:211], v[8:11]
	v_mfma_f32_16x16x32_bf16 v[4:7], v[156:159], v[232:235], v[4:7]
	v_mfma_f32_16x16x32_bf16 v[0:3], v[184:187], v[232:235], v[0:3]
	s_setprio 0
	s_barrier
	s_mov_b32 m0, s62
	v_lshl_add_u64 v[144:145], v[248:249], 0, s[8:9]
	global_load_lds_dwordx4 v[248:249], off
	s_mov_b32 m0, s63
	v_lshl_add_u64 v[146:147], v[250:251], 0, s[8:9]
	global_load_lds_dwordx4 v[250:251], off
	s_waitcnt vmcnt(6)
	s_barrier
	s_setprio 1
	v_mfma_f32_16x16x32_bf16 v[56:59], v[216:219], v[188:191], v[56:59]
	v_mfma_f32_16x16x32_bf16 v[60:63], v[224:227], v[188:191], v[60:63]
	v_mfma_f32_16x16x32_bf16 v[64:67], v[216:219], v[196:199], v[64:67]
	v_mfma_f32_16x16x32_bf16 v[72:75], v[224:227], v[196:199], v[72:75]
	v_mfma_f32_16x16x32_bf16 v[76:79], v[216:219], v[204:207], v[76:79]
	v_mfma_f32_16x16x32_bf16 v[80:83], v[224:227], v[204:207], v[80:83]
	v_mfma_f32_16x16x32_bf16 v[88:91], v[216:219], v[212:215], v[88:91]
	v_mfma_f32_16x16x32_bf16 v[92:95], v[224:227], v[212:215], v[92:95]
	v_mfma_f32_16x16x32_bf16 v[56:59], v[220:223], v[192:195], v[56:59]
	v_mfma_f32_16x16x32_bf16 v[60:63], v[228:231], v[192:195], v[60:63]
	v_mfma_f32_16x16x32_bf16 v[64:67], v[220:223], v[200:203], v[64:67]
	v_mfma_f32_16x16x32_bf16 v[72:75], v[228:231], v[200:203], v[72:75]
	v_mfma_f32_16x16x32_bf16 v[76:79], v[220:223], v[208:211], v[76:79]
	v_mfma_f32_16x16x32_bf16 v[80:83], v[228:231], v[208:211], v[80:83]
	v_mfma_f32_16x16x32_bf16 v[88:91], v[220:223], v[232:235], v[88:91]
	v_mfma_f32_16x16x32_bf16 v[92:95], v[228:231], v[232:235], v[92:95]
	s_setprio 0
	s_barrier
	s_branch .LBB0_634
